# nt hint on the in-proj MG gate stores only (100 MB, first consumed in phase 8); other in-proj outputs keep the default policy
# speedup vs baseline: 1.0083x; 1.0071x over previous
.LBB0_275:
	s_lshl_b32 s23, s10, 8
	s_lshl_b32 s71, s2, 8
	s_or_b32 s27, s23, s43
	s_cmp_gt_i32 s10, 5
	s_cselect_b64 s[54:55], -1, 0
	v_add_u32_e32 v158, s71, v1
	v_or_b32_e32 v156, s27, v162
	s_mov_b64 s[2:3], -1
	s_and_b64 vcc, exec, s[54:55]
	s_cbranch_vccz .LBB0_297
	s_cmp_gt_u32 s10, 7
	s_cbranch_scc0 .LBB0_294
	s_cmp_lt_u32 s10, 11
	s_cbranch_scc1 .LBB0_279
	v_mul_f32_e32 v130, 0xbfb8aa3b, v126
	v_exp_f32_e32 v130, v130
	v_mul_f32_e32 v131, 0xbfb8aa3b, v122
	v_exp_f32_e32 v131, v131
	v_mul_f32_e32 v133, 0xbfb8aa3b, v123
	v_add_f32_e32 v130, 1.0, v130
	v_rcp_f32_e32 v132, v130
	v_mul_f32_e32 v130, 0xbfb8aa3b, v127
	v_exp_f32_e32 v130, v130
	v_exp_f32_e32 v133, v133
	v_add_f32_e32 v131, 1.0, v131
	v_rcp_f32_e32 v136, v131
	v_add_f32_e32 v130, 1.0, v130
	v_mul_f32_e32 v131, 0xbfb8aa3b, v128
	v_rcp_f32_e32 v137, v130
	v_add_f32_e32 v130, 1.0, v133
	v_exp_f32_e32 v131, v131
	v_mul_f32_e32 v133, 0xbfb8aa3b, v124
	v_exp_f32_e32 v133, v133
	v_rcp_f32_e32 v146, v130
	v_add_f32_e32 v130, 1.0, v131
	v_mul_f32_e32 v131, 0xbfb8aa3b, v129
	v_rcp_f32_e32 v160, v130
	v_add_f32_e32 v130, 1.0, v133
	v_exp_f32_e32 v131, v131
	v_mul_f32_e32 v133, 0xbfb8aa3b, v125
	v_exp_f32_e32 v133, v133
	v_rcp_f32_e32 v161, v130
	v_add_f32_e32 v130, 1.0, v131
	v_rcp_f32_e32 v174, v130
	v_add_f32_e32 v130, 1.0, v133
	v_ashrrev_i32_e32 v159, 31, v158
	v_rcp_f32_e32 v133, v130
	v_lshlrev_b64 v[130:131], 12, v[158:159]
	v_lshl_add_u64 v[130:131], s[84:85], 0, v[130:131]
	v_mov_b32_e32 v157, v147
	v_lshl_add_u64 v[134:135], v[156:157], 1, v[130:131]
	v_add_co_u32_e32 v134, vcc, 0x89fe000, v134
	s_mov_b64 s[2:3], 0
	s_nop 0
	v_addc_co_u32_e32 v135, vcc, 0, v135, vcc
	v_cvt_pk_bf16_f32 v130, v132, v137
	v_cvt_pk_bf16_f32 v131, v160, v174
	v_cvt_pk_bf16_f32 v132, v136, v146
	v_cvt_pk_bf16_f32 v133, v161, v133
	global_store_dwordx4 v[134:135], v[130:133], off offset:2560 nt

.LBB0_299:
	v_or_b32_e32 v130, s23, v168
	v_or_b32_e32 v134, 0x80, v130
	s_mov_b64 s[2:3], -1
	s_and_b64 vcc, exec, s[54:55]
	s_cbranch_vccz .LBB0_638
	s_cmp_gt_u32 s10, 7
	s_cbranch_scc0 .LBB0_319
	s_cmp_lt_u32 s10, 11
	s_cbranch_scc1 .LBB0_303
	v_mul_f32_e32 v122, 0xbfb8aa3b, v118
	v_exp_f32_e32 v122, v122
	v_mul_f32_e32 v123, 0xbfb8aa3b, v114
	v_exp_f32_e32 v123, v123
	v_mul_f32_e32 v125, 0xbfb8aa3b, v115
	v_add_f32_e32 v122, 1.0, v122
	v_rcp_f32_e32 v124, v122
	v_mul_f32_e32 v122, 0xbfb8aa3b, v119
	v_exp_f32_e32 v122, v122
	v_exp_f32_e32 v125, v125
	v_add_f32_e32 v123, 1.0, v123
	v_rcp_f32_e32 v128, v123
	v_add_f32_e32 v122, 1.0, v122
	v_mul_f32_e32 v123, 0xbfb8aa3b, v120
	v_rcp_f32_e32 v129, v122
	v_add_f32_e32 v122, 1.0, v125
	v_exp_f32_e32 v123, v123
	v_mul_f32_e32 v125, 0xbfb8aa3b, v116
	v_exp_f32_e32 v125, v125
	v_rcp_f32_e32 v132, v122
	v_add_f32_e32 v122, 1.0, v123
	v_mul_f32_e32 v123, 0xbfb8aa3b, v121
	v_rcp_f32_e32 v133, v122
	v_add_f32_e32 v122, 1.0, v125
	v_exp_f32_e32 v123, v123
	v_mul_f32_e32 v125, 0xbfb8aa3b, v117
	v_exp_f32_e32 v125, v125
	v_rcp_f32_e32 v135, v122
	v_add_f32_e32 v122, 1.0, v123
	v_rcp_f32_e32 v136, v122
	v_add_f32_e32 v122, 1.0, v125
	v_ashrrev_i32_e32 v159, 31, v158
	v_rcp_f32_e32 v125, v122
	v_lshlrev_b64 v[122:123], 12, v[158:159]
	v_lshl_add_u64 v[122:123], s[84:85], 0, v[122:123]
	v_mov_b32_e32 v131, v147
	v_lshl_add_u64 v[126:127], v[130:131], 1, v[122:123]
	v_add_co_u32_e32 v126, vcc, 0x89fe000, v126
	s_mov_b64 s[2:3], 0
	s_nop 0
	v_addc_co_u32_e32 v127, vcc, 0, v127, vcc
	v_cvt_pk_bf16_f32 v122, v124, v129
	v_cvt_pk_bf16_f32 v123, v133, v136
	v_cvt_pk_bf16_f32 v124, v128, v132
	v_cvt_pk_bf16_f32 v125, v135, v125
	global_store_dwordx4 v[126:127], v[122:125], off offset:2816 nt

.LBB0_323:
	s_cmp_gt_u32 s10, 7
	s_cbranch_scc0 .LBB0_341
	s_cmp_lt_u32 s10, 11
	s_cbranch_scc1 .LBB0_326
	v_mul_f32_e32 v114, 0xbfb8aa3b, v110
	v_exp_f32_e32 v114, v114
	v_mul_f32_e32 v115, 0xbfb8aa3b, v106
	v_exp_f32_e32 v115, v115
	v_mul_f32_e32 v117, 0xbfb8aa3b, v107
	v_add_f32_e32 v114, 1.0, v114
	v_rcp_f32_e32 v116, v114
	v_mul_f32_e32 v114, 0xbfb8aa3b, v111
	v_exp_f32_e32 v114, v114
	v_exp_f32_e32 v117, v117
	v_add_f32_e32 v115, 1.0, v115
	v_rcp_f32_e32 v120, v115
	v_add_f32_e32 v114, 1.0, v114
	v_mul_f32_e32 v115, 0xbfb8aa3b, v112
	v_rcp_f32_e32 v121, v114
	v_add_f32_e32 v114, 1.0, v117
	v_exp_f32_e32 v115, v115
	v_mul_f32_e32 v117, 0xbfb8aa3b, v108
	v_exp_f32_e32 v117, v117
	v_rcp_f32_e32 v124, v114
	v_add_f32_e32 v114, 1.0, v115
	v_mul_f32_e32 v115, 0xbfb8aa3b, v113
	v_rcp_f32_e32 v125, v114
	v_add_f32_e32 v114, 1.0, v117
	v_exp_f32_e32 v115, v115
	v_mul_f32_e32 v117, 0xbfb8aa3b, v109
	v_exp_f32_e32 v117, v117
	v_rcp_f32_e32 v126, v114
	v_add_f32_e32 v114, 1.0, v115
	v_rcp_f32_e32 v127, v114
	v_add_f32_e32 v114, 1.0, v117
	v_ashrrev_i32_e32 v123, 31, v122
	v_rcp_f32_e32 v117, v114
	v_lshlrev_b64 v[114:115], 12, v[122:123]
	v_lshl_add_u64 v[114:115], s[84:85], 0, v[114:115]
	v_mov_b32_e32 v146, v156
	v_lshl_add_u64 v[118:119], v[146:147], 1, v[114:115]
	v_add_co_u32_e32 v118, vcc, 0x89fe000, v118
	s_mov_b64 s[2:3], 0
	s_nop 0
	v_addc_co_u32_e32 v119, vcc, 0, v119, vcc
	v_cvt_pk_bf16_f32 v114, v116, v121
	v_cvt_pk_bf16_f32 v115, v125, v127
	v_cvt_pk_bf16_f32 v116, v120, v124
	v_cvt_pk_bf16_f32 v117, v126, v117
	global_store_dwordx4 v[118:119], v[114:117], off offset:2560 nt

.LBB0_345:
	s_cmp_gt_u32 s10, 7
	s_cbranch_scc0 .LBB0_364
	s_cmp_lt_u32 s10, 11
	s_cbranch_scc1 .LBB0_348
	v_mul_f32_e32 v106, 0xbfb8aa3b, v102
	v_exp_f32_e32 v106, v106
	v_mul_f32_e32 v107, 0xbfb8aa3b, v98
	v_exp_f32_e32 v107, v107
	v_mul_f32_e32 v109, 0xbfb8aa3b, v99
	v_add_f32_e32 v106, 1.0, v106
	v_rcp_f32_e32 v108, v106
	v_mul_f32_e32 v106, 0xbfb8aa3b, v103
	v_exp_f32_e32 v106, v106
	v_exp_f32_e32 v109, v109
	v_add_f32_e32 v107, 1.0, v107
	v_rcp_f32_e32 v112, v107
	v_add_f32_e32 v106, 1.0, v106
	v_mul_f32_e32 v107, 0xbfb8aa3b, v104
	v_rcp_f32_e32 v113, v106
	v_add_f32_e32 v106, 1.0, v109
	v_exp_f32_e32 v107, v107
	v_mul_f32_e32 v109, 0xbfb8aa3b, v100
	v_exp_f32_e32 v109, v109
	v_rcp_f32_e32 v114, v106
	v_add_f32_e32 v106, 1.0, v107
	v_mul_f32_e32 v107, 0xbfb8aa3b, v105
	v_rcp_f32_e32 v115, v106
	v_add_f32_e32 v106, 1.0, v109
	v_exp_f32_e32 v107, v107
	v_mul_f32_e32 v109, 0xbfb8aa3b, v101
	v_exp_f32_e32 v109, v109
	v_rcp_f32_e32 v116, v106
	v_add_f32_e32 v106, 1.0, v107
	v_rcp_f32_e32 v117, v106
	v_add_f32_e32 v106, 1.0, v109
	v_ashrrev_i32_e32 v123, 31, v122
	v_rcp_f32_e32 v109, v106
	v_lshlrev_b64 v[106:107], 12, v[122:123]
	v_lshl_add_u64 v[106:107], s[84:85], 0, v[106:107]
	v_mov_b32_e32 v146, v130
	v_lshl_add_u64 v[110:111], v[146:147], 1, v[106:107]
	v_add_co_u32_e32 v110, vcc, 0x89fe000, v110
	s_mov_b64 s[2:3], 0
	s_nop 0
	v_addc_co_u32_e32 v111, vcc, 0, v111, vcc
	v_cvt_pk_bf16_f32 v106, v108, v113
	v_cvt_pk_bf16_f32 v107, v115, v117
	v_cvt_pk_bf16_f32 v108, v112, v114
	v_cvt_pk_bf16_f32 v109, v116, v109
	global_store_dwordx4 v[110:111], v[106:109], off offset:2816 nt

.LBB0_368:
	s_cmp_gt_u32 s10, 7
	s_cbranch_scc0 .LBB0_386
	s_cmp_lt_u32 s10, 11
	s_cbranch_scc1 .LBB0_371
	v_mul_f32_e32 v98, 0xbfb8aa3b, v94
	v_exp_f32_e32 v98, v98
	v_mul_f32_e32 v99, 0xbfb8aa3b, v90
	v_exp_f32_e32 v99, v99
	v_mul_f32_e32 v101, 0xbfb8aa3b, v91
	v_add_f32_e32 v98, 1.0, v98
	v_rcp_f32_e32 v100, v98
	v_mul_f32_e32 v98, 0xbfb8aa3b, v95
	v_exp_f32_e32 v98, v98
	v_exp_f32_e32 v101, v101
	v_add_f32_e32 v99, 1.0, v99
	v_rcp_f32_e32 v104, v99
	v_add_f32_e32 v98, 1.0, v98
	v_mul_f32_e32 v99, 0xbfb8aa3b, v96
	v_rcp_f32_e32 v105, v98
	v_add_f32_e32 v98, 1.0, v101
	v_exp_f32_e32 v99, v99
	v_mul_f32_e32 v101, 0xbfb8aa3b, v92
	v_exp_f32_e32 v101, v101
	v_rcp_f32_e32 v108, v98
	v_add_f32_e32 v98, 1.0, v99
	v_mul_f32_e32 v99, 0xbfb8aa3b, v97
	v_rcp_f32_e32 v109, v98
	v_add_f32_e32 v98, 1.0, v101
	v_exp_f32_e32 v99, v99
	v_mul_f32_e32 v101, 0xbfb8aa3b, v93
	v_exp_f32_e32 v101, v101
	v_rcp_f32_e32 v110, v98
	v_add_f32_e32 v98, 1.0, v99
	v_rcp_f32_e32 v111, v98
	v_add_f32_e32 v98, 1.0, v101
	v_ashrrev_i32_e32 v107, 31, v106
	v_rcp_f32_e32 v101, v98
	v_lshlrev_b64 v[98:99], 12, v[106:107]
	v_lshl_add_u64 v[98:99], s[84:85], 0, v[98:99]
	v_mov_b32_e32 v146, v156
	v_lshl_add_u64 v[102:103], v[146:147], 1, v[98:99]
	v_add_co_u32_e32 v102, vcc, 0x89fe000, v102
	s_mov_b64 s[2:3], 0
	s_nop 0
	v_addc_co_u32_e32 v103, vcc, 0, v103, vcc
	v_cvt_pk_bf16_f32 v98, v100, v105
	v_cvt_pk_bf16_f32 v99, v109, v111
	v_cvt_pk_bf16_f32 v100, v104, v108
	v_cvt_pk_bf16_f32 v101, v110, v101
	global_store_dwordx4 v[102:103], v[98:101], off offset:2560 nt

.LBB0_390:
	s_cmp_gt_u32 s10, 7
	s_cbranch_scc0 .LBB0_409
	s_cmp_lt_u32 s10, 11
	s_cbranch_scc1 .LBB0_393
	v_mul_f32_e32 v90, 0xbfb8aa3b, v86
	v_exp_f32_e32 v90, v90
	v_mul_f32_e32 v91, 0xbfb8aa3b, v82
	v_exp_f32_e32 v91, v91
	v_mul_f32_e32 v93, 0xbfb8aa3b, v83
	v_add_f32_e32 v90, 1.0, v90
	v_rcp_f32_e32 v92, v90
	v_mul_f32_e32 v90, 0xbfb8aa3b, v87
	v_exp_f32_e32 v90, v90
	v_exp_f32_e32 v93, v93
	v_add_f32_e32 v91, 1.0, v91
	v_rcp_f32_e32 v96, v91
	v_add_f32_e32 v90, 1.0, v90
	v_mul_f32_e32 v91, 0xbfb8aa3b, v88
	v_rcp_f32_e32 v97, v90
	v_add_f32_e32 v90, 1.0, v93
	v_exp_f32_e32 v91, v91
	v_mul_f32_e32 v93, 0xbfb8aa3b, v84
	v_exp_f32_e32 v93, v93
	v_rcp_f32_e32 v98, v90
	v_add_f32_e32 v90, 1.0, v91
	v_mul_f32_e32 v91, 0xbfb8aa3b, v89
	v_rcp_f32_e32 v99, v90
	v_add_f32_e32 v90, 1.0, v93
	v_exp_f32_e32 v91, v91
	v_mul_f32_e32 v93, 0xbfb8aa3b, v85
	v_exp_f32_e32 v93, v93
	v_rcp_f32_e32 v100, v90
	v_add_f32_e32 v90, 1.0, v91
	v_rcp_f32_e32 v101, v90
	v_add_f32_e32 v90, 1.0, v93
	v_ashrrev_i32_e32 v107, 31, v106
	v_rcp_f32_e32 v93, v90
	v_lshlrev_b64 v[90:91], 12, v[106:107]
	v_lshl_add_u64 v[90:91], s[84:85], 0, v[90:91]
	v_mov_b32_e32 v146, v130
	v_lshl_add_u64 v[94:95], v[146:147], 1, v[90:91]
	v_add_co_u32_e32 v94, vcc, 0x89fe000, v94
	s_mov_b64 s[2:3], 0
	s_nop 0
	v_addc_co_u32_e32 v95, vcc, 0, v95, vcc
	v_cvt_pk_bf16_f32 v90, v92, v97
	v_cvt_pk_bf16_f32 v91, v99, v101
	v_cvt_pk_bf16_f32 v92, v96, v98
	v_cvt_pk_bf16_f32 v93, v100, v93
	global_store_dwordx4 v[94:95], v[90:93], off offset:2816 nt

.LBB0_413:
	s_cmp_gt_u32 s10, 7
	s_cbranch_scc0 .LBB0_431
	s_cmp_lt_u32 s10, 11
	s_cbranch_scc1 .LBB0_416
	v_mul_f32_e32 v82, 0xbfb8aa3b, v78
	v_exp_f32_e32 v82, v82
	v_mul_f32_e32 v83, 0xbfb8aa3b, v74
	v_exp_f32_e32 v83, v83
	v_mul_f32_e32 v85, 0xbfb8aa3b, v75
	v_add_f32_e32 v82, 1.0, v82
	v_rcp_f32_e32 v84, v82
	v_mul_f32_e32 v82, 0xbfb8aa3b, v79
	v_exp_f32_e32 v82, v82
	v_exp_f32_e32 v85, v85
	v_add_f32_e32 v83, 1.0, v83
	v_rcp_f32_e32 v88, v83
	v_add_f32_e32 v82, 1.0, v82
	v_mul_f32_e32 v83, 0xbfb8aa3b, v80
	v_rcp_f32_e32 v89, v82
	v_add_f32_e32 v82, 1.0, v85
	v_exp_f32_e32 v83, v83
	v_mul_f32_e32 v85, 0xbfb8aa3b, v76
	v_exp_f32_e32 v85, v85
	v_rcp_f32_e32 v92, v82
	v_add_f32_e32 v82, 1.0, v83
	v_mul_f32_e32 v83, 0xbfb8aa3b, v81
	v_rcp_f32_e32 v93, v82
	v_add_f32_e32 v82, 1.0, v85
	v_exp_f32_e32 v83, v83
	v_mul_f32_e32 v85, 0xbfb8aa3b, v77
	v_exp_f32_e32 v85, v85
	v_rcp_f32_e32 v94, v82
	v_add_f32_e32 v82, 1.0, v83
	v_rcp_f32_e32 v95, v82
	v_add_f32_e32 v82, 1.0, v85
	v_ashrrev_i32_e32 v91, 31, v90
	v_rcp_f32_e32 v85, v82
	v_lshlrev_b64 v[82:83], 12, v[90:91]
	v_lshl_add_u64 v[82:83], s[84:85], 0, v[82:83]
	v_mov_b32_e32 v146, v156
	v_lshl_add_u64 v[86:87], v[146:147], 1, v[82:83]
	v_add_co_u32_e32 v86, vcc, 0x89fe000, v86
	s_mov_b64 s[2:3], 0
	s_nop 0
	v_addc_co_u32_e32 v87, vcc, 0, v87, vcc
	v_cvt_pk_bf16_f32 v82, v84, v89
	v_cvt_pk_bf16_f32 v83, v93, v95
	v_cvt_pk_bf16_f32 v84, v88, v92
	v_cvt_pk_bf16_f32 v85, v94, v85
	global_store_dwordx4 v[86:87], v[82:85], off offset:2560 nt

.LBB0_435:
	s_cmp_gt_u32 s10, 7
	s_cbranch_scc0 .LBB0_454
	s_cmp_lt_u32 s10, 11
	s_cbranch_scc1 .LBB0_438
	v_mul_f32_e32 v74, 0xbfb8aa3b, v70
	v_exp_f32_e32 v74, v74
	v_mul_f32_e32 v75, 0xbfb8aa3b, v66
	v_exp_f32_e32 v75, v75
	v_mul_f32_e32 v77, 0xbfb8aa3b, v67
	v_add_f32_e32 v74, 1.0, v74
	v_rcp_f32_e32 v76, v74
	v_mul_f32_e32 v74, 0xbfb8aa3b, v71
	v_exp_f32_e32 v74, v74
	v_exp_f32_e32 v77, v77
	v_add_f32_e32 v75, 1.0, v75
	v_rcp_f32_e32 v80, v75
	v_add_f32_e32 v74, 1.0, v74
	v_mul_f32_e32 v75, 0xbfb8aa3b, v72
	v_rcp_f32_e32 v81, v74
	v_add_f32_e32 v74, 1.0, v77
	v_exp_f32_e32 v75, v75
	v_mul_f32_e32 v77, 0xbfb8aa3b, v68
	v_exp_f32_e32 v77, v77
	v_rcp_f32_e32 v82, v74
	v_add_f32_e32 v74, 1.0, v75
	v_mul_f32_e32 v75, 0xbfb8aa3b, v73
	v_rcp_f32_e32 v83, v74
	v_add_f32_e32 v74, 1.0, v77
	v_exp_f32_e32 v75, v75
	v_mul_f32_e32 v77, 0xbfb8aa3b, v69
	v_exp_f32_e32 v77, v77
	v_rcp_f32_e32 v84, v74
	v_add_f32_e32 v74, 1.0, v75
	v_rcp_f32_e32 v85, v74
	v_add_f32_e32 v74, 1.0, v77
	v_ashrrev_i32_e32 v91, 31, v90
	v_rcp_f32_e32 v77, v74
	v_lshlrev_b64 v[74:75], 12, v[90:91]
	v_lshl_add_u64 v[74:75], s[84:85], 0, v[74:75]
	v_mov_b32_e32 v146, v130
	v_lshl_add_u64 v[78:79], v[146:147], 1, v[74:75]
	v_add_co_u32_e32 v78, vcc, 0x89fe000, v78
	s_mov_b64 s[2:3], 0
	s_nop 0
	v_addc_co_u32_e32 v79, vcc, 0, v79, vcc
	v_cvt_pk_bf16_f32 v74, v76, v81
	v_cvt_pk_bf16_f32 v75, v83, v85
	v_cvt_pk_bf16_f32 v76, v80, v82
	v_cvt_pk_bf16_f32 v77, v84, v77
	global_store_dwordx4 v[78:79], v[74:77], off offset:2816 nt

.LBB0_458:
	s_cmp_gt_u32 s10, 7
	s_cbranch_scc0 .LBB0_476
	s_cmp_lt_u32 s10, 11
	s_cbranch_scc1 .LBB0_461
	v_mul_f32_e32 v66, 0xbfb8aa3b, v62
	v_exp_f32_e32 v66, v66
	v_mul_f32_e32 v67, 0xbfb8aa3b, v58
	v_exp_f32_e32 v67, v67
	v_mul_f32_e32 v69, 0xbfb8aa3b, v59
	v_add_f32_e32 v66, 1.0, v66
	v_rcp_f32_e32 v68, v66
	v_mul_f32_e32 v66, 0xbfb8aa3b, v63
	v_exp_f32_e32 v66, v66
	v_exp_f32_e32 v69, v69
	v_add_f32_e32 v67, 1.0, v67
	v_rcp_f32_e32 v72, v67
	v_add_f32_e32 v66, 1.0, v66
	v_mul_f32_e32 v67, 0xbfb8aa3b, v64
	v_rcp_f32_e32 v73, v66
	v_add_f32_e32 v66, 1.0, v69
	v_exp_f32_e32 v67, v67
	v_mul_f32_e32 v69, 0xbfb8aa3b, v60
	v_exp_f32_e32 v69, v69
	v_rcp_f32_e32 v76, v66
	v_add_f32_e32 v66, 1.0, v67
	v_mul_f32_e32 v67, 0xbfb8aa3b, v65
	v_rcp_f32_e32 v77, v66
	v_add_f32_e32 v66, 1.0, v69
	v_exp_f32_e32 v67, v67
	v_mul_f32_e32 v69, 0xbfb8aa3b, v61
	v_exp_f32_e32 v69, v69
	v_rcp_f32_e32 v78, v66
	v_add_f32_e32 v66, 1.0, v67
	v_rcp_f32_e32 v79, v66
	v_add_f32_e32 v66, 1.0, v69
	v_ashrrev_i32_e32 v75, 31, v74
	v_rcp_f32_e32 v69, v66
	v_lshlrev_b64 v[66:67], 12, v[74:75]
	v_lshl_add_u64 v[66:67], s[84:85], 0, v[66:67]
	v_mov_b32_e32 v146, v156
	v_lshl_add_u64 v[70:71], v[146:147], 1, v[66:67]
	v_add_co_u32_e32 v70, vcc, 0x89fe000, v70
	s_mov_b64 s[2:3], 0
	s_nop 0
	v_addc_co_u32_e32 v71, vcc, 0, v71, vcc
	v_cvt_pk_bf16_f32 v66, v68, v73
	v_cvt_pk_bf16_f32 v67, v77, v79
	v_cvt_pk_bf16_f32 v68, v72, v76
	v_cvt_pk_bf16_f32 v69, v78, v69
	global_store_dwordx4 v[70:71], v[66:69], off offset:2560 nt

.LBB0_480:
	s_cmp_gt_u32 s10, 7
	s_cbranch_scc0 .LBB0_499
	s_cmp_lt_u32 s10, 11
	s_cbranch_scc1 .LBB0_483
	v_mul_f32_e32 v58, 0xbfb8aa3b, v54
	v_exp_f32_e32 v58, v58
	v_mul_f32_e32 v59, 0xbfb8aa3b, v50
	v_exp_f32_e32 v59, v59
	v_mul_f32_e32 v61, 0xbfb8aa3b, v51
	v_add_f32_e32 v58, 1.0, v58
	v_rcp_f32_e32 v60, v58
	v_mul_f32_e32 v58, 0xbfb8aa3b, v55
	v_exp_f32_e32 v58, v58
	v_exp_f32_e32 v61, v61
	v_add_f32_e32 v59, 1.0, v59
	v_rcp_f32_e32 v64, v59
	v_add_f32_e32 v58, 1.0, v58
	v_mul_f32_e32 v59, 0xbfb8aa3b, v56
	v_rcp_f32_e32 v65, v58
	v_add_f32_e32 v58, 1.0, v61
	v_exp_f32_e32 v59, v59
	v_mul_f32_e32 v61, 0xbfb8aa3b, v52
	v_exp_f32_e32 v61, v61
	v_rcp_f32_e32 v66, v58
	v_add_f32_e32 v58, 1.0, v59
	v_mul_f32_e32 v59, 0xbfb8aa3b, v57
	v_rcp_f32_e32 v67, v58
	v_add_f32_e32 v58, 1.0, v61
	v_exp_f32_e32 v59, v59
	v_mul_f32_e32 v61, 0xbfb8aa3b, v53
	v_exp_f32_e32 v61, v61
	v_rcp_f32_e32 v68, v58
	v_add_f32_e32 v58, 1.0, v59
	v_rcp_f32_e32 v69, v58
	v_add_f32_e32 v58, 1.0, v61
	v_ashrrev_i32_e32 v75, 31, v74
	v_rcp_f32_e32 v61, v58
	v_lshlrev_b64 v[58:59], 12, v[74:75]
	v_lshl_add_u64 v[58:59], s[84:85], 0, v[58:59]
	v_mov_b32_e32 v146, v130
	v_lshl_add_u64 v[62:63], v[146:147], 1, v[58:59]
	v_add_co_u32_e32 v62, vcc, 0x89fe000, v62
	s_mov_b64 s[2:3], 0
	s_nop 0
	v_addc_co_u32_e32 v63, vcc, 0, v63, vcc
	v_cvt_pk_bf16_f32 v58, v60, v65
	v_cvt_pk_bf16_f32 v59, v67, v69
	v_cvt_pk_bf16_f32 v60, v64, v66
	v_cvt_pk_bf16_f32 v61, v68, v61
	global_store_dwordx4 v[62:63], v[58:61], off offset:2816 nt

.LBB0_503:
	s_cmp_gt_u32 s10, 7
	s_cbranch_scc0 .LBB0_521
	s_cmp_lt_u32 s10, 11
	s_cbranch_scc1 .LBB0_506
	v_mul_f32_e32 v50, 0xbfb8aa3b, v46
	v_exp_f32_e32 v50, v50
	v_mul_f32_e32 v51, 0xbfb8aa3b, v42
	v_exp_f32_e32 v51, v51
	v_mul_f32_e32 v53, 0xbfb8aa3b, v43
	v_add_f32_e32 v50, 1.0, v50
	v_rcp_f32_e32 v52, v50
	v_mul_f32_e32 v50, 0xbfb8aa3b, v47
	v_exp_f32_e32 v50, v50
	v_exp_f32_e32 v53, v53
	v_add_f32_e32 v51, 1.0, v51
	v_rcp_f32_e32 v56, v51
	v_add_f32_e32 v50, 1.0, v50
	v_mul_f32_e32 v51, 0xbfb8aa3b, v48
	v_rcp_f32_e32 v57, v50
	v_add_f32_e32 v50, 1.0, v53
	v_exp_f32_e32 v51, v51
	v_mul_f32_e32 v53, 0xbfb8aa3b, v44
	v_exp_f32_e32 v53, v53
	v_rcp_f32_e32 v60, v50
	v_add_f32_e32 v50, 1.0, v51
	v_mul_f32_e32 v51, 0xbfb8aa3b, v49
	v_rcp_f32_e32 v61, v50
	v_add_f32_e32 v50, 1.0, v53
	v_exp_f32_e32 v51, v51
	v_mul_f32_e32 v53, 0xbfb8aa3b, v45
	v_exp_f32_e32 v53, v53
	v_rcp_f32_e32 v62, v50
	v_add_f32_e32 v50, 1.0, v51
	v_rcp_f32_e32 v63, v50
	v_add_f32_e32 v50, 1.0, v53
	v_ashrrev_i32_e32 v59, 31, v58
	v_rcp_f32_e32 v53, v50
	v_lshlrev_b64 v[50:51], 12, v[58:59]
	v_lshl_add_u64 v[50:51], s[84:85], 0, v[50:51]
	v_mov_b32_e32 v146, v156
	v_lshl_add_u64 v[54:55], v[146:147], 1, v[50:51]
	v_add_co_u32_e32 v54, vcc, 0x89fe000, v54
	s_mov_b64 s[2:3], 0
	s_nop 0
	v_addc_co_u32_e32 v55, vcc, 0, v55, vcc
	v_cvt_pk_bf16_f32 v50, v52, v57
	v_cvt_pk_bf16_f32 v51, v61, v63
	v_cvt_pk_bf16_f32 v52, v56, v60
	v_cvt_pk_bf16_f32 v53, v62, v53
	global_store_dwordx4 v[54:55], v[50:53], off offset:2560 nt

.LBB0_525:
	s_cmp_gt_u32 s10, 7
	s_cbranch_scc0 .LBB0_544
	s_cmp_lt_u32 s10, 11
	s_cbranch_scc1 .LBB0_528
	v_mul_f32_e32 v42, 0xbfb8aa3b, v38
	v_exp_f32_e32 v42, v42
	v_mul_f32_e32 v43, 0xbfb8aa3b, v34
	v_exp_f32_e32 v43, v43
	v_mul_f32_e32 v45, 0xbfb8aa3b, v35
	v_add_f32_e32 v42, 1.0, v42
	v_rcp_f32_e32 v44, v42
	v_mul_f32_e32 v42, 0xbfb8aa3b, v39
	v_exp_f32_e32 v42, v42
	v_exp_f32_e32 v45, v45
	v_add_f32_e32 v43, 1.0, v43
	v_rcp_f32_e32 v48, v43
	v_add_f32_e32 v42, 1.0, v42
	v_mul_f32_e32 v43, 0xbfb8aa3b, v40
	v_rcp_f32_e32 v49, v42
	v_add_f32_e32 v42, 1.0, v45
	v_exp_f32_e32 v43, v43
	v_mul_f32_e32 v45, 0xbfb8aa3b, v36
	v_exp_f32_e32 v45, v45
	v_rcp_f32_e32 v50, v42
	v_add_f32_e32 v42, 1.0, v43
	v_mul_f32_e32 v43, 0xbfb8aa3b, v41
	v_rcp_f32_e32 v51, v42
	v_add_f32_e32 v42, 1.0, v45
	v_exp_f32_e32 v43, v43
	v_mul_f32_e32 v45, 0xbfb8aa3b, v37
	v_exp_f32_e32 v45, v45
	v_rcp_f32_e32 v52, v42
	v_add_f32_e32 v42, 1.0, v43
	v_rcp_f32_e32 v53, v42
	v_add_f32_e32 v42, 1.0, v45
	v_ashrrev_i32_e32 v59, 31, v58
	v_rcp_f32_e32 v45, v42
	v_lshlrev_b64 v[42:43], 12, v[58:59]
	v_lshl_add_u64 v[42:43], s[84:85], 0, v[42:43]
	v_mov_b32_e32 v146, v130
	v_lshl_add_u64 v[46:47], v[146:147], 1, v[42:43]
	v_add_co_u32_e32 v46, vcc, 0x89fe000, v46
	s_mov_b64 s[2:3], 0
	s_nop 0
	v_addc_co_u32_e32 v47, vcc, 0, v47, vcc
	v_cvt_pk_bf16_f32 v42, v44, v49
	v_cvt_pk_bf16_f32 v43, v51, v53
	v_cvt_pk_bf16_f32 v44, v48, v50
	v_cvt_pk_bf16_f32 v45, v52, v45
	global_store_dwordx4 v[46:47], v[42:45], off offset:2816 nt

.LBB0_548:
	s_cmp_gt_u32 s10, 7
	s_cbranch_scc0 .LBB0_566
	s_cmp_lt_u32 s10, 11
	s_cbranch_scc1 .LBB0_551
	v_mul_f32_e32 v34, 0xbfb8aa3b, v30
	v_exp_f32_e32 v34, v34
	v_mul_f32_e32 v35, 0xbfb8aa3b, v26
	v_exp_f32_e32 v35, v35
	v_mul_f32_e32 v37, 0xbfb8aa3b, v27
	v_add_f32_e32 v34, 1.0, v34
	v_rcp_f32_e32 v36, v34
	v_mul_f32_e32 v34, 0xbfb8aa3b, v31
	v_exp_f32_e32 v34, v34
	v_exp_f32_e32 v37, v37
	v_add_f32_e32 v35, 1.0, v35
	v_rcp_f32_e32 v40, v35
	v_add_f32_e32 v34, 1.0, v34
	v_mul_f32_e32 v35, 0xbfb8aa3b, v32
	v_rcp_f32_e32 v41, v34
	v_add_f32_e32 v34, 1.0, v37
	v_exp_f32_e32 v35, v35
	v_mul_f32_e32 v37, 0xbfb8aa3b, v28
	v_exp_f32_e32 v37, v37
	v_rcp_f32_e32 v44, v34
	v_add_f32_e32 v34, 1.0, v35
	v_mul_f32_e32 v35, 0xbfb8aa3b, v33
	v_rcp_f32_e32 v45, v34
	v_add_f32_e32 v34, 1.0, v37
	v_exp_f32_e32 v35, v35
	v_mul_f32_e32 v37, 0xbfb8aa3b, v29
	v_exp_f32_e32 v37, v37
	v_rcp_f32_e32 v46, v34
	v_add_f32_e32 v34, 1.0, v35
	v_rcp_f32_e32 v47, v34
	v_add_f32_e32 v34, 1.0, v37
	v_ashrrev_i32_e32 v43, 31, v42
	v_rcp_f32_e32 v37, v34
	v_lshlrev_b64 v[34:35], 12, v[42:43]
	v_lshl_add_u64 v[34:35], s[84:85], 0, v[34:35]
	v_mov_b32_e32 v146, v156
	v_lshl_add_u64 v[38:39], v[146:147], 1, v[34:35]
	v_add_co_u32_e32 v38, vcc, 0x89fe000, v38
	s_mov_b64 s[2:3], 0
	s_nop 0
	v_addc_co_u32_e32 v39, vcc, 0, v39, vcc
	v_cvt_pk_bf16_f32 v34, v36, v41
	v_cvt_pk_bf16_f32 v35, v45, v47
	v_cvt_pk_bf16_f32 v36, v40, v44
	v_cvt_pk_bf16_f32 v37, v46, v37
	global_store_dwordx4 v[38:39], v[34:37], off offset:2560 nt

.LBB0_570:
	s_cmp_gt_u32 s10, 7
	s_cbranch_scc0 .LBB0_589
	s_cmp_lt_u32 s10, 11
	s_cbranch_scc1 .LBB0_573
	v_mul_f32_e32 v26, 0xbfb8aa3b, v22
	v_exp_f32_e32 v26, v26
	v_mul_f32_e32 v27, 0xbfb8aa3b, v18
	v_exp_f32_e32 v27, v27
	v_mul_f32_e32 v29, 0xbfb8aa3b, v19
	v_add_f32_e32 v26, 1.0, v26
	v_rcp_f32_e32 v28, v26
	v_mul_f32_e32 v26, 0xbfb8aa3b, v23
	v_exp_f32_e32 v26, v26
	v_exp_f32_e32 v29, v29
	v_add_f32_e32 v27, 1.0, v27
	v_rcp_f32_e32 v32, v27
	v_add_f32_e32 v26, 1.0, v26
	v_mul_f32_e32 v27, 0xbfb8aa3b, v24
	v_rcp_f32_e32 v33, v26
	v_add_f32_e32 v26, 1.0, v29
	v_exp_f32_e32 v27, v27
	v_mul_f32_e32 v29, 0xbfb8aa3b, v20
	v_exp_f32_e32 v29, v29
	v_rcp_f32_e32 v34, v26
	v_add_f32_e32 v26, 1.0, v27
	v_mul_f32_e32 v27, 0xbfb8aa3b, v25
	v_rcp_f32_e32 v35, v26
	v_add_f32_e32 v26, 1.0, v29
	v_exp_f32_e32 v27, v27
	v_mul_f32_e32 v29, 0xbfb8aa3b, v21
	v_exp_f32_e32 v29, v29
	v_rcp_f32_e32 v36, v26
	v_add_f32_e32 v26, 1.0, v27
	v_rcp_f32_e32 v37, v26
	v_add_f32_e32 v26, 1.0, v29
	v_ashrrev_i32_e32 v43, 31, v42
	v_rcp_f32_e32 v29, v26
	v_lshlrev_b64 v[26:27], 12, v[42:43]
	v_lshl_add_u64 v[26:27], s[84:85], 0, v[26:27]
	v_mov_b32_e32 v146, v130
	v_lshl_add_u64 v[30:31], v[146:147], 1, v[26:27]
	v_add_co_u32_e32 v30, vcc, 0x89fe000, v30
	s_mov_b64 s[2:3], 0
	s_nop 0
	v_addc_co_u32_e32 v31, vcc, 0, v31, vcc
	v_cvt_pk_bf16_f32 v26, v28, v33
	v_cvt_pk_bf16_f32 v27, v35, v37
	v_cvt_pk_bf16_f32 v28, v32, v34
	v_cvt_pk_bf16_f32 v29, v36, v29
	global_store_dwordx4 v[30:31], v[26:29], off offset:2816 nt

.LBB0_593:
	s_cmp_gt_u32 s10, 7
	s_cbranch_scc0 .LBB0_611
	s_cmp_lt_u32 s10, 11
	s_cbranch_scc1 .LBB0_596
	v_mul_f32_e32 v18, 0xbfb8aa3b, v14
	v_exp_f32_e32 v18, v18
	v_mul_f32_e32 v19, 0xbfb8aa3b, v10
	v_exp_f32_e32 v19, v19
	v_mul_f32_e32 v21, 0xbfb8aa3b, v11
	v_add_f32_e32 v18, 1.0, v18
	v_rcp_f32_e32 v20, v18
	v_mul_f32_e32 v18, 0xbfb8aa3b, v15
	v_exp_f32_e32 v18, v18
	v_exp_f32_e32 v21, v21
	v_add_f32_e32 v19, 1.0, v19
	v_rcp_f32_e32 v24, v19
	v_add_f32_e32 v18, 1.0, v18
	v_mul_f32_e32 v19, 0xbfb8aa3b, v16
	v_rcp_f32_e32 v25, v18
	v_add_f32_e32 v18, 1.0, v21
	v_exp_f32_e32 v19, v19
	v_mul_f32_e32 v21, 0xbfb8aa3b, v12
	v_exp_f32_e32 v21, v21
	v_rcp_f32_e32 v28, v18
	v_add_f32_e32 v18, 1.0, v19
	v_mul_f32_e32 v19, 0xbfb8aa3b, v17
	v_rcp_f32_e32 v29, v18
	v_add_f32_e32 v18, 1.0, v21
	v_exp_f32_e32 v19, v19
	v_mul_f32_e32 v21, 0xbfb8aa3b, v13
	v_exp_f32_e32 v21, v21
	v_rcp_f32_e32 v30, v18
	v_add_f32_e32 v18, 1.0, v19
	v_rcp_f32_e32 v31, v18
	v_add_f32_e32 v18, 1.0, v21
	v_ashrrev_i32_e32 v27, 31, v26
	v_rcp_f32_e32 v21, v18
	v_lshlrev_b64 v[18:19], 12, v[26:27]
	v_lshl_add_u64 v[18:19], s[84:85], 0, v[18:19]
	v_mov_b32_e32 v146, v156
	v_lshl_add_u64 v[22:23], v[146:147], 1, v[18:19]
	v_add_co_u32_e32 v22, vcc, 0x89fe000, v22
	s_mov_b64 s[2:3], 0
	s_nop 0
	v_addc_co_u32_e32 v23, vcc, 0, v23, vcc
	v_cvt_pk_bf16_f32 v18, v20, v25
	v_cvt_pk_bf16_f32 v19, v29, v31
	v_cvt_pk_bf16_f32 v20, v24, v28
	v_cvt_pk_bf16_f32 v21, v30, v21
	global_store_dwordx4 v[22:23], v[18:21], off offset:2560 nt

.LBB0_615:
	s_cmp_gt_u32 s10, 7
	s_cbranch_scc0 .LBB0_634
	s_cmp_lt_u32 s10, 11
	s_cbranch_scc1 .LBB0_618
	v_mul_f32_e32 v10, 0xbfb8aa3b, v6
	v_exp_f32_e32 v10, v10
	v_mul_f32_e32 v11, 0xbfb8aa3b, v2
	v_exp_f32_e32 v11, v11
	v_mul_f32_e32 v13, 0xbfb8aa3b, v3
	v_add_f32_e32 v10, 1.0, v10
	v_rcp_f32_e32 v12, v10
	v_mul_f32_e32 v10, 0xbfb8aa3b, v7
	v_exp_f32_e32 v10, v10
	v_exp_f32_e32 v13, v13
	v_add_f32_e32 v11, 1.0, v11
	v_rcp_f32_e32 v16, v11
	v_add_f32_e32 v10, 1.0, v10
	v_mul_f32_e32 v11, 0xbfb8aa3b, v8
	v_rcp_f32_e32 v17, v10
	v_add_f32_e32 v10, 1.0, v13
	v_exp_f32_e32 v11, v11
	v_mul_f32_e32 v13, 0xbfb8aa3b, v4
	v_exp_f32_e32 v13, v13
	v_rcp_f32_e32 v18, v10
	v_add_f32_e32 v10, 1.0, v11
	v_mul_f32_e32 v11, 0xbfb8aa3b, v9
	v_rcp_f32_e32 v19, v10
	v_add_f32_e32 v10, 1.0, v13
	v_exp_f32_e32 v11, v11
	v_mul_f32_e32 v13, 0xbfb8aa3b, v5
	v_exp_f32_e32 v13, v13
	v_rcp_f32_e32 v20, v10
	v_add_f32_e32 v10, 1.0, v11
	v_rcp_f32_e32 v21, v10
	v_add_f32_e32 v10, 1.0, v13
	v_ashrrev_i32_e32 v27, 31, v26
	v_rcp_f32_e32 v13, v10
	v_lshlrev_b64 v[10:11], 12, v[26:27]
	v_lshl_add_u64 v[10:11], s[84:85], 0, v[10:11]
	v_mov_b32_e32 v146, v130
	v_lshl_add_u64 v[14:15], v[146:147], 1, v[10:11]
	v_add_co_u32_e32 v14, vcc, 0x89fe000, v14
	s_mov_b64 s[2:3], 0
	s_nop 0
	v_addc_co_u32_e32 v15, vcc, 0, v15, vcc
	v_cvt_pk_bf16_f32 v10, v12, v17
	v_cvt_pk_bf16_f32 v11, v19, v21
	v_cvt_pk_bf16_f32 v12, v16, v18
	v_cvt_pk_bf16_f32 v13, v20, v13
	global_store_dwordx4 v[14:15], v[10:13], off offset:2816 nt
